# c9 = c7 + nt (streaming) policy on the QKVG stores of the HGRN input projection epilogue
# speedup vs baseline: 1.0014x; 1.0014x over previous
.LBB0_670:
	v_lshl_add_u32 v126, s6, 8, v159
	v_ashrrev_i32_e32 v127, 31, v126
	v_lshlrev_b64 v[122:123], 14, v[126:127]
	v_ashrrev_i32_e32 v147, 31, v146
	v_lshl_add_u64 v[122:123], s[14:15], 0, v[122:123]
	v_lshl_add_u64 v[128:129], v[146:147], 1, v[122:123]
	v_cndmask_b32_e64 v122, 0, 1, s[30:31]
	v_cmp_ne_u32_e64 s[6:7], 1, v122
	s_andn2_b64 vcc, exec, s[30:31]
	global_store_dwordx4 v[128:129], v[130:133], off nt
	s_cbranch_vccz .LBB0_765
	s_and_b64 vcc, exec, s[4:5]
	s_cbranch_vccz .LBB0_766

.LBB0_676:
	s_and_b64 vcc, exec, s[6:7]
	global_store_dwordx4 v[128:129], v[122:125], off offset:256 nt
	s_cbranch_vccz .LBB0_769

.LBB0_682:
	v_or_b32_e32 v106, 16, v126
	v_ashrrev_i32_e32 v107, 31, v106
	v_lshlrev_b64 v[106:107], 14, v[106:107]
	v_lshl_add_u64 v[106:107], s[14:15], 0, v[106:107]
	v_lshl_add_u64 v[110:111], v[146:147], 1, v[106:107]
	s_and_b64 vcc, exec, s[6:7]
	global_store_dwordx4 v[110:111], v[114:117], off nt
	s_cbranch_vccz .LBB0_773
	s_and_b64 vcc, exec, s[4:5]
	s_cbranch_vccz .LBB0_774

.LBB0_687:
	s_and_b64 vcc, exec, s[6:7]
	global_store_dwordx4 v[110:111], v[106:109], off offset:256 nt
	s_cbranch_vccz .LBB0_778

.LBB0_693:
	v_or_b32_e32 v90, 32, v126
	v_ashrrev_i32_e32 v91, 31, v90
	v_lshlrev_b64 v[90:91], 14, v[90:91]
	v_lshl_add_u64 v[90:91], s[14:15], 0, v[90:91]
	v_lshl_add_u64 v[94:95], v[146:147], 1, v[90:91]
	s_and_b64 vcc, exec, s[6:7]
	global_store_dwordx4 v[94:95], v[98:101], off nt
	s_cbranch_vccz .LBB0_782
	s_and_b64 vcc, exec, s[4:5]
	s_cbranch_vccz .LBB0_783

.LBB0_698:
	s_and_b64 vcc, exec, s[6:7]
	global_store_dwordx4 v[94:95], v[90:93], off offset:256 nt
	s_cbranch_vccz .LBB0_787

.LBB0_704:
	v_or_b32_e32 v74, 48, v126
	v_ashrrev_i32_e32 v75, 31, v74
	v_lshlrev_b64 v[74:75], 14, v[74:75]
	v_lshl_add_u64 v[74:75], s[14:15], 0, v[74:75]
	v_lshl_add_u64 v[78:79], v[146:147], 1, v[74:75]
	s_and_b64 vcc, exec, s[6:7]
	global_store_dwordx4 v[78:79], v[82:85], off nt
	s_cbranch_vccz .LBB0_791
	s_and_b64 vcc, exec, s[4:5]
	s_cbranch_vccz .LBB0_792

.LBB0_709:
	s_and_b64 vcc, exec, s[6:7]
	global_store_dwordx4 v[78:79], v[74:77], off offset:256 nt
	s_cbranch_vccz .LBB0_796

.LBB0_715:
	v_lshlrev_b64 v[58:59], 14, v[126:127]
	v_lshl_add_u64 v[58:59], s[14:15], 0, v[58:59]
	v_lshl_add_u64 v[62:63], v[146:147], 1, v[58:59]
	v_add_co_u32_e32 v58, vcc, 0x200000, v62
	s_nop 1
	v_addc_co_u32_e32 v59, vcc, 0, v63, vcc
	s_and_b64 vcc, exec, s[6:7]
	global_store_dwordx4 v[58:59], v[66:69], off nt
	s_cbranch_vccz .LBB0_800
	s_and_b64 vcc, exec, s[4:5]
	s_cbranch_vccz .LBB0_801

.LBB0_721:
	s_mov_b64 s[28:29], 0x200000
	v_lshl_add_u64 v[50:51], v[62:63], 0, s[28:29]
	s_and_b64 vcc, exec, s[6:7]
	global_store_dwordx4 v[50:51], v[58:61], off offset:256 nt
	s_cbranch_vccz .LBB0_804
	s_and_b64 vcc, exec, s[4:5]
	s_cbranch_vccz .LBB0_805

.LBB0_727:
	v_lshlrev_b64 v[42:43], 14, v[126:127]
	v_lshl_add_u64 v[42:43], s[14:15], 0, v[42:43]
	v_lshl_add_u64 v[46:47], v[146:147], 1, v[42:43]
	v_add_co_u32_e32 v42, vcc, 0x240000, v46
	s_nop 1
	v_addc_co_u32_e32 v43, vcc, 0, v47, vcc
	s_and_b64 vcc, exec, s[6:7]
	global_store_dwordx4 v[42:43], v[50:53], off nt
	s_cbranch_vccz .LBB0_808
	s_and_b64 vcc, exec, s[4:5]
	s_cbranch_vccz .LBB0_809

.LBB0_733:
	s_mov_b64 s[28:29], 0x240000
	v_lshl_add_u64 v[34:35], v[46:47], 0, s[28:29]
	s_and_b64 vcc, exec, s[6:7]
	global_store_dwordx4 v[34:35], v[42:45], off offset:256 nt
	s_cbranch_vccz .LBB0_812
	s_and_b64 vcc, exec, s[4:5]
	s_cbranch_vccz .LBB0_813

.LBB0_739:
	v_lshlrev_b64 v[26:27], 14, v[126:127]
	v_lshl_add_u64 v[26:27], s[14:15], 0, v[26:27]
	v_lshl_add_u64 v[30:31], v[146:147], 1, v[26:27]
	v_add_co_u32_e32 v26, vcc, 0x280000, v30
	s_nop 1
	v_addc_co_u32_e32 v27, vcc, 0, v31, vcc
	s_and_b64 vcc, exec, s[6:7]
	global_store_dwordx4 v[26:27], v[34:37], off nt
	s_cbranch_vccz .LBB0_816
	s_and_b64 vcc, exec, s[4:5]
	s_cbranch_vccz .LBB0_817

.LBB0_745:
	s_mov_b64 s[28:29], 0x280000
	v_lshl_add_u64 v[18:19], v[30:31], 0, s[28:29]
	s_and_b64 vcc, exec, s[6:7]
	global_store_dwordx4 v[18:19], v[26:29], off offset:256 nt
	s_cbranch_vccz .LBB0_820
	s_and_b64 vcc, exec, s[4:5]
	s_cbranch_vccz .LBB0_821

.LBB0_751:
	v_lshlrev_b64 v[10:11], 14, v[126:127]
	v_lshl_add_u64 v[10:11], s[14:15], 0, v[10:11]
	v_lshl_add_u64 v[14:15], v[146:147], 1, v[10:11]
	v_add_co_u32_e32 v10, vcc, 0x2c0000, v14
	s_nop 1
	v_addc_co_u32_e32 v11, vcc, 0, v15, vcc
	s_and_b64 vcc, exec, s[6:7]
	global_store_dwordx4 v[10:11], v[18:21], off nt
	s_cbranch_vccz .LBB0_824
	s_and_b64 vcc, exec, s[4:5]
	s_cbranch_vccz .LBB0_825

.LBB0_757:
	s_mov_b64 s[4:5], 0x2c0000
	v_lshl_add_u64 v[2:3], v[14:15], 0, s[4:5]
	s_andn2_b64 vcc, exec, s[2:3]
	s_mov_b64 s[2:3], -1
	global_store_dwordx4 v[2:3], v[10:13], off offset:256 nt
	s_cbranch_vccnz .LBB0_646
	s_andn2_b64 vcc, exec, s[12:13]
	s_cbranch_vccnz .LBB0_645
	s_barrier
	s_branch .LBB0_645

.LBB0_768:
	v_cvt_pk_f16_f32 v122, v118, v119
	v_cvt_pk_f16_f32 v123, v120, v121
	v_cvt_pk_f16_f32 v124, v114, v115
	v_cvt_pk_f16_f32 v125, v116, v117
	s_and_b64 vcc, exec, s[6:7]
	global_store_dwordx4 v[128:129], v[122:125], off offset:256 nt
	s_cbranch_vccnz .LBB0_677

.LBB0_777:
	v_cvt_pk_f16_f32 v106, v102, v103
	v_cvt_pk_f16_f32 v107, v104, v105
	v_cvt_pk_f16_f32 v108, v98, v99
	v_cvt_pk_f16_f32 v109, v100, v101
	s_and_b64 vcc, exec, s[6:7]
	global_store_dwordx4 v[110:111], v[106:109], off offset:256 nt
	s_cbranch_vccnz .LBB0_688

.LBB0_786:
	v_cvt_pk_f16_f32 v90, v86, v87
	v_cvt_pk_f16_f32 v91, v88, v89
	v_cvt_pk_f16_f32 v92, v82, v83
	v_cvt_pk_f16_f32 v93, v84, v85
	s_and_b64 vcc, exec, s[6:7]
	global_store_dwordx4 v[94:95], v[90:93], off offset:256 nt
	s_cbranch_vccnz .LBB0_699

.LBB0_795:
	v_cvt_pk_f16_f32 v74, v70, v71
	v_cvt_pk_f16_f32 v75, v72, v73
	v_cvt_pk_f16_f32 v76, v66, v67
	v_cvt_pk_f16_f32 v77, v68, v69
	s_and_b64 vcc, exec, s[6:7]
	global_store_dwordx4 v[78:79], v[74:77], off offset:256 nt
	s_cbranch_vccnz .LBB0_710
